# mla_up epilogue: nt (non-temporal) hint on its 32 loads and 16 stores per wave
# baseline (speedup 1.0000x reference)
; __device__ __forceinline__ float sigmoidf_(float g) { return __builtin_amdgcn_rcpf(1.f + __expf(-g)); }
; __device__ __forceinline__ u32x4 pack8(const f32x4& a, const f32x4& b) { u32x4 w; w.x = cvt_pk_bf16(a[0], a[1]); w.y = cvt_pk_bf16(a[2], a[3]); w.z = cvt_pk_bf16(b[0], b[1]); w.w = cvt_pk_bf16(b[2], b[3]); return w; }
; __device__ __forceinline__ void unpack8(const u32x4& w, float (&v)[8]) { v[0] = bf_lo(w.x); v[1] = bf_hi(w.x); v[2] = bf_lo(w.y); v[3] = bf_hi(w.y); v[4] = bf_lo(w.z); v[5] = bf_hi(w.z); v[6] = bf_lo(w.w); v[7] = bf_hi(w.w); }
;     __device__ __forceinline__ void apply(const Ld& d, int row, int c0, int, int, int, const f32x4& a0, const f32x4& b0, const f32x4& a1, const f32x4& b1) const { half(d.g0, row, c0, a0, b0); half(d.g1, row, c0 + 128, a1, b1); }
;     __device__ __forceinline__ void half(const u32x4& gw, const u32x4& pw, int row, int col, const f32x4& a, const f32x4& b) const {
;         float g[8]; unpack8(gw, g); float p[8]; unpack8(pw, p);
;         f32x4 r0, r1;
; #pragma unroll
;         for (int i = 0; i < 4; ++i) { r0[i] = a[i] * sigmoidf_(g[i]) + p[i]; r1[i] = b[i] * sigmoidf_(g[4 + i]) + p[4 + i]; }
;         *(u32x4*)(merged + (size_t)row * 1024 + col) = pack8(r0, r1);
;     }
;     __device__ __forceinline__ void apply(const Ld& d, int row, int c0, int, int, int, const f32x4& a0, const f32x4& b0, const f32x4& a1, const f32x4& b1) const { half(d.g0, d.p0, row, c0, a0, b0); half(d.g1, d.p1, row, c0 + 128, a1, b1); }
.LBB0_283:
	s_and_b64 vcc, exec, s[0:1]
	s_cbranch_vccz .LBB0_285
	v_lshl_or_b32 v134, s71, 8, v241
	v_ashrrev_i32_e32 v135, 31, v134
	v_readlane_b32 s0, v254, 62
	v_lshlrev_b64 v[164:165], 1, v[134:135]
	v_readlane_b32 s1, v254, 63
	v_mov_b64_e32 v[168:169], s[74:75]
	s_nop 0
	v_lshl_add_u64 v[162:163], s[0:1], 0, v[164:165]
	s_lshl_b32 s0, s63, 8
	v_add_u32_e32 v166, s0, v17
	v_mad_i64_i32 v[134:135], s[22:23], v166, s29, v[168:169]
	v_lshl_add_u64 v[134:135], v[134:135], 0, v[164:165]
	v_add_co_u32_e32 v136, vcc, 0x1000, v134
	v_or_b32_e32 v0, 16, v166
	s_nop 0
	v_addc_co_u32_e32 v137, vcc, 0, v135, vcc
	global_load_dwordx4 v[158:161], v[136:137], off offset:3072 nt
	global_load_dwordx4 v[150:153], v[136:137], off offset:3328 nt
	global_load_dwordx4 v[170:173], v[134:135], off offset:2048 nt
	global_load_dwordx4 v[154:157], v[134:135], off offset:2304 nt
	v_mad_i64_i32 v[134:135], s[22:23], v0, s29, v[168:169]
	v_lshl_add_u64 v[134:135], v[134:135], 0, v[164:165]
	v_add_co_u32_e32 v136, vcc, 0x1000, v134
	v_ashrrev_i32_e32 v167, 31, v166
	s_nop 0
	v_addc_co_u32_e32 v137, vcc, 0, v135, vcc
	global_load_dwordx4 v[146:149], v[136:137], off offset:3072 nt
	global_load_dwordx4 v[138:141], v[136:137], off offset:3328 nt
	global_load_dwordx4 v[142:145], v[134:135], off offset:2048 nt
	s_nop 0
	global_load_dwordx4 v[134:137], v[134:135], off offset:2304 nt
	s_waitcnt vmcnt(0)
	v_lshlrev_b32_e32 v0, 16, v158
	v_mul_f32_e32 v0, 0xbfb8aa3b, v0
	v_exp_f32_e32 v0, v0
	v_lshlrev_b32_e32 v175, 16, v160
	v_lshlrev_b32_e32 v177, 16, v170
	v_and_b32_e32 v158, 0xffff0000, v158
	v_add_f32_e32 v0, 1.0, v0
	v_rcp_f32_e32 v0, v0
	v_lshlrev_b32_e32 v179, 16, v172
	v_and_b32_e32 v160, 0xffff0000, v160
	v_and_b32_e32 v170, 0xffff0000, v170
	v_fmac_f32_e32 v177, v130, v0
	v_mul_f32_e32 v0, 0xbfb8aa3b, v175
	v_exp_f32_e32 v0, v0
	v_lshlrev_b32_e32 v174, 16, v159
	v_and_b32_e32 v172, 0xffff0000, v172
	v_lshlrev_b32_e32 v176, 16, v161
	v_add_f32_e32 v0, 1.0, v0
	v_rcp_f32_e32 v0, v0
	v_lshlrev_b32_e32 v178, 16, v171
	v_and_b32_e32 v159, 0xffff0000, v159
	v_lshlrev_b32_e32 v180, 16, v173
	v_fmac_f32_e32 v179, v126, v0
	v_mul_f32_e32 v0, 0xbfb8aa3b, v158
	v_exp_f32_e32 v0, v0
	v_and_b32_e32 v161, 0xffff0000, v161
	v_and_b32_e32 v171, 0xffff0000, v171
	v_and_b32_e32 v173, 0xffff0000, v173
	v_add_f32_e32 v0, 1.0, v0
	v_rcp_f32_e32 v0, v0
	s_nop 0
	v_fmac_f32_e32 v170, v131, v0
	v_mul_f32_e32 v0, 0xbfb8aa3b, v160
	v_exp_f32_e32 v0, v0
	v_cvt_pk_bf16_f32 v158, v177, v170
	s_nop 0
	v_add_f32_e32 v0, 1.0, v0
	v_rcp_f32_e32 v0, v0
	s_nop 0
	v_fmac_f32_e32 v172, v127, v0
	v_mul_f32_e32 v0, 0xbfb8aa3b, v174
	v_exp_f32_e32 v0, v0
	v_add_u32_e32 v174, s0, v236
	v_add_f32_e32 v0, 1.0, v0
	v_rcp_f32_e32 v0, v0
	s_nop 0
	v_fmac_f32_e32 v178, v132, v0
	v_mul_f32_e32 v0, 0xbfb8aa3b, v176
	v_exp_f32_e32 v0, v0
	s_nop 0
	v_add_f32_e32 v0, 1.0, v0
	v_rcp_f32_e32 v0, v0
	s_nop 0
	v_fmac_f32_e32 v180, v128, v0
	v_mul_f32_e32 v0, 0xbfb8aa3b, v159
	v_exp_f32_e32 v0, v0
	s_nop 0
	v_add_f32_e32 v0, 1.0, v0
	v_rcp_f32_e32 v0, v0
	s_nop 0
	v_fmac_f32_e32 v171, v133, v0
	v_mul_f32_e32 v0, 0xbfb8aa3b, v161
	v_exp_f32_e32 v0, v0
	v_cvt_pk_bf16_f32 v159, v178, v171
	v_lshlrev_b64 v[170:171], 11, v[166:167]
	v_cvt_pk_bf16_f32 v160, v179, v172
	v_add_f32_e32 v0, 1.0, v0
	v_rcp_f32_e32 v0, v0
	v_lshl_add_u64 v[170:171], v[162:163], 0, v[170:171]
	v_lshlrev_b32_e32 v172, 16, v156
	v_and_b32_e32 v156, 0xffff0000, v156
	v_fmac_f32_e32 v173, v129, v0
	v_lshlrev_b32_e32 v0, 16, v150
	v_mul_f32_e32 v0, 0xbfb8aa3b, v0
	v_exp_f32_e32 v0, v0
	v_cvt_pk_bf16_f32 v161, v180, v173
	global_store_dwordx4 v[170:171], v[158:161], off nt
	v_and_b32_e32 v150, 0xffff0000, v150
	v_add_f32_e32 v0, 1.0, v0
	v_rcp_f32_e32 v0, v0
	v_lshlrev_b32_e32 v159, 16, v152
	v_lshlrev_b32_e32 v161, 16, v154
	v_and_b32_e32 v152, 0xffff0000, v152
	v_fmac_f32_e32 v161, v122, v0
	v_mul_f32_e32 v0, 0xbfb8aa3b, v159
	v_exp_f32_e32 v0, v0
	v_and_b32_e32 v154, 0xffff0000, v154
	v_lshlrev_b32_e32 v158, 16, v151
	v_lshlrev_b32_e32 v160, 16, v153
	v_add_f32_e32 v0, 1.0, v0
	v_rcp_f32_e32 v0, v0
	v_lshlrev_b32_e32 v167, 16, v155
	v_and_b32_e32 v151, 0xffff0000, v151
	v_lshlrev_b32_e32 v173, 16, v157
	v_fmac_f32_e32 v172, v118, v0
	v_mul_f32_e32 v0, 0xbfb8aa3b, v150
	v_exp_f32_e32 v0, v0
	v_and_b32_e32 v153, 0xffff0000, v153
	v_and_b32_e32 v155, 0xffff0000, v155
	v_and_b32_e32 v157, 0xffff0000, v157
	v_add_f32_e32 v0, 1.0, v0
	v_rcp_f32_e32 v0, v0
	s_nop 0
	v_fmac_f32_e32 v154, v123, v0
	v_mul_f32_e32 v0, 0xbfb8aa3b, v152
	v_exp_f32_e32 v0, v0
	v_cvt_pk_bf16_f32 v150, v161, v154
	v_lshlrev_b32_e32 v154, 16, v142
	v_and_b32_e32 v142, 0xffff0000, v142
	v_add_f32_e32 v0, 1.0, v0
	v_rcp_f32_e32 v0, v0
	s_nop 0
	v_fmac_f32_e32 v156, v119, v0
	v_mul_f32_e32 v0, 0xbfb8aa3b, v158
	v_exp_f32_e32 v0, v0
	s_nop 0
	v_add_f32_e32 v0, 1.0, v0
	v_rcp_f32_e32 v0, v0
	s_nop 0
	v_fmac_f32_e32 v167, v124, v0
	v_mul_f32_e32 v0, 0xbfb8aa3b, v160
	v_exp_f32_e32 v0, v0
	s_nop 0
	v_add_f32_e32 v0, 1.0, v0
	v_rcp_f32_e32 v0, v0
	s_nop 0
	v_fmac_f32_e32 v173, v120, v0
	v_mul_f32_e32 v0, 0xbfb8aa3b, v151
	v_exp_f32_e32 v0, v0
	s_nop 0
	v_add_f32_e32 v0, 1.0, v0
	v_rcp_f32_e32 v0, v0
	s_nop 0
	v_fmac_f32_e32 v155, v125, v0
	v_mul_f32_e32 v0, 0xbfb8aa3b, v153
	v_exp_f32_e32 v0, v0
	v_cvt_pk_bf16_f32 v151, v167, v155
	v_cvt_pk_bf16_f32 v152, v172, v156
	v_lshlrev_b32_e32 v156, 16, v144
	v_add_f32_e32 v0, 1.0, v0
	v_rcp_f32_e32 v0, v0
	v_and_b32_e32 v144, 0xffff0000, v144
	v_lshlrev_b32_e32 v155, 16, v143
	v_and_b32_e32 v143, 0xffff0000, v143
	v_fmac_f32_e32 v157, v121, v0
	v_lshlrev_b32_e32 v0, 16, v146
	v_mul_f32_e32 v0, 0xbfb8aa3b, v0
	v_exp_f32_e32 v0, v0
; __device__ __forceinline__ float sigmoidf_(float g) { return __builtin_amdgcn_rcpf(1.f + __expf(-g)); }
; __device__ __forceinline__ u32x4 pack8(const f32x4& a, const f32x4& b) { u32x4 w; w.x = cvt_pk_bf16(a[0], a[1]); w.y = cvt_pk_bf16(a[2], a[3]); w.z = cvt_pk_bf16(b[0], b[1]); w.w = cvt_pk_bf16(b[2], b[3]); return w; }
; __device__ __forceinline__ void unpack8(const u32x4& w, float (&v)[8]) { v[0] = bf_lo(w.x); v[1] = bf_hi(w.x); v[2] = bf_lo(w.y); v[3] = bf_hi(w.y); v[4] = bf_lo(w.z); v[5] = bf_hi(w.z); v[6] = bf_lo(w.w); v[7] = bf_hi(w.w); }
;     __device__ __forceinline__ void apply(const Ld& d, int row, int c0, int, int, int, const f32x4& a0, const f32x4& b0, const f32x4& a1, const f32x4& b1) const { half(d.g0, row, c0, a0, b0); half(d.g1, row, c0 + 128, a1, b1); }
;     __device__ __forceinline__ void half(const u32x4& gw, const u32x4& pw, int row, int col, const f32x4& a, const f32x4& b) const {
;         float g[8]; unpack8(gw, g); float p[8]; unpack8(pw, p);
;         f32x4 r0, r1;
; #pragma unroll
;         for (int i = 0; i < 4; ++i) { r0[i] = a[i] * sigmoidf_(g[i]) + p[i]; r1[i] = b[i] * sigmoidf_(g[4 + i]) + p[4 + i]; }
;         *(u32x4*)(merged + (size_t)row * 1024 + col) = pack8(r0, r1);
;     }
;     __device__ __forceinline__ void apply(const Ld& d, int row, int c0, int, int, int, const f32x4& a0, const f32x4& b0, const f32x4& a1, const f32x4& b1) const { half(d.g0, d.p0, row, c0, a0, b0); half(d.g1, d.p1, row, c0 + 128, a1, b1); }
	v_cvt_pk_bf16_f32 v153, v173, v157
	global_store_dwordx4 v[170:171], v[150:153], off offset:256 nt
	v_and_b32_e32 v146, 0xffff0000, v146
	v_add_f32_e32 v0, 1.0, v0
	v_rcp_f32_e32 v0, v0
	v_lshlrev_b32_e32 v152, 16, v148
	v_and_b32_e32 v148, 0xffff0000, v148
	v_lshlrev_b32_e32 v151, 16, v147
	v_fmac_f32_e32 v154, v114, v0
	v_mul_f32_e32 v0, 0xbfb8aa3b, v152
	v_exp_f32_e32 v0, v0
	v_lshlrev_b32_e32 v153, 16, v149
	v_and_b32_e32 v147, 0xffff0000, v147
	v_lshlrev_b32_e32 v157, 16, v145
	v_add_f32_e32 v0, 1.0, v0
	v_rcp_f32_e32 v0, v0
	v_and_b32_e32 v149, 0xffff0000, v149
	v_and_b32_e32 v145, 0xffff0000, v145
	v_add_u32_e32 v150, s0, v235
	v_fmac_f32_e32 v156, v110, v0
	v_mul_f32_e32 v0, 0xbfb8aa3b, v146
	v_exp_f32_e32 v0, v0
	s_nop 0
	v_add_f32_e32 v0, 1.0, v0
	v_rcp_f32_e32 v0, v0
	s_nop 0
	v_fmac_f32_e32 v142, v115, v0
	v_mul_f32_e32 v0, 0xbfb8aa3b, v148
	v_exp_f32_e32 v0, v0
	v_cvt_pk_bf16_f32 v142, v154, v142
	v_lshlrev_b32_e32 v148, 16, v135
	v_and_b32_e32 v135, 0xffff0000, v135
	v_add_f32_e32 v0, 1.0, v0
	v_rcp_f32_e32 v0, v0
	s_nop 0
	v_fmac_f32_e32 v144, v111, v0
	v_mul_f32_e32 v0, 0xbfb8aa3b, v151
	v_exp_f32_e32 v0, v0
	v_ashrrev_i32_e32 v151, 31, v150
	v_add_f32_e32 v0, 1.0, v0
	v_rcp_f32_e32 v0, v0
	s_nop 0
	v_fmac_f32_e32 v155, v116, v0
	v_mul_f32_e32 v0, 0xbfb8aa3b, v153
	v_exp_f32_e32 v0, v0
	s_nop 0
	v_add_f32_e32 v0, 1.0, v0
	v_rcp_f32_e32 v0, v0
	s_nop 0
	v_fmac_f32_e32 v157, v112, v0
	v_mul_f32_e32 v0, 0xbfb8aa3b, v147
	v_exp_f32_e32 v0, v0
	v_lshlrev_b64 v[146:147], 11, v[150:151]
	v_lshl_add_u64 v[146:147], v[162:163], 0, v[146:147]
	v_lshlrev_b32_e32 v150, 16, v137
	v_add_f32_e32 v0, 1.0, v0
	v_rcp_f32_e32 v0, v0
	v_and_b32_e32 v137, 0xffff0000, v137
	v_fmac_f32_e32 v143, v117, v0
	v_mul_f32_e32 v0, 0xbfb8aa3b, v149
	v_exp_f32_e32 v0, v0
	v_cvt_pk_bf16_f32 v143, v155, v143
	v_cvt_pk_bf16_f32 v144, v156, v144
	v_lshlrev_b32_e32 v149, 16, v136
	v_add_f32_e32 v0, 1.0, v0
	v_rcp_f32_e32 v0, v0
	v_and_b32_e32 v136, 0xffff0000, v136
	v_fmac_f32_e32 v145, v113, v0
	v_lshlrev_b32_e32 v0, 16, v138
	v_mul_f32_e32 v0, 0xbfb8aa3b, v0
	v_exp_f32_e32 v0, v0
	v_cvt_pk_bf16_f32 v145, v157, v145
	global_store_dwordx4 v[146:147], v[142:145], off nt
	v_and_b32_e32 v138, 0xffff0000, v138
	v_add_f32_e32 v0, 1.0, v0
	v_rcp_f32_e32 v0, v0
	v_lshlrev_b32_e32 v143, 16, v140
	v_lshlrev_b32_e32 v145, 16, v134
	v_and_b32_e32 v140, 0xffff0000, v140
	v_fmac_f32_e32 v145, v106, v0
	v_mul_f32_e32 v0, 0xbfb8aa3b, v143
	v_exp_f32_e32 v0, v0
	v_and_b32_e32 v134, 0xffff0000, v134
	v_lshlrev_b32_e32 v142, 16, v139
	v_lshlrev_b32_e32 v144, 16, v141
	v_add_f32_e32 v0, 1.0, v0
	v_rcp_f32_e32 v0, v0
	v_and_b32_e32 v139, 0xffff0000, v139
	v_and_b32_e32 v141, 0xffff0000, v141
	v_fmac_f32_e32 v149, v102, v0
	v_mul_f32_e32 v0, 0xbfb8aa3b, v138
	v_exp_f32_e32 v0, v0
	s_nop 0
	v_add_f32_e32 v0, 1.0, v0
	v_rcp_f32_e32 v0, v0
	s_nop 0
	v_fmac_f32_e32 v134, v107, v0
	v_mul_f32_e32 v0, 0xbfb8aa3b, v140
	v_exp_f32_e32 v0, v0
	v_cvt_pk_bf16_f32 v134, v145, v134
	s_nop 0
	v_add_f32_e32 v0, 1.0, v0
	v_rcp_f32_e32 v0, v0
	s_nop 0
	v_fmac_f32_e32 v136, v103, v0
	v_mul_f32_e32 v0, 0xbfb8aa3b, v142
	v_exp_f32_e32 v0, v0
	s_nop 0
	v_add_f32_e32 v0, 1.0, v0
	v_rcp_f32_e32 v0, v0
	s_nop 0
	v_fmac_f32_e32 v148, v108, v0
	v_mul_f32_e32 v0, 0xbfb8aa3b, v144
	v_exp_f32_e32 v0, v0
	s_nop 0
	v_add_f32_e32 v0, 1.0, v0
	v_rcp_f32_e32 v0, v0
	s_nop 0
	v_fmac_f32_e32 v150, v104, v0
	v_mul_f32_e32 v0, 0xbfb8aa3b, v139
	v_exp_f32_e32 v0, v0
	s_nop 0
	v_add_f32_e32 v0, 1.0, v0
	v_rcp_f32_e32 v0, v0
	s_nop 0
	v_fmac_f32_e32 v135, v109, v0
	v_mul_f32_e32 v0, 0xbfb8aa3b, v141
	v_exp_f32_e32 v0, v0
	v_cvt_pk_bf16_f32 v135, v148, v135
	v_cvt_pk_bf16_f32 v136, v149, v136
	s_nop 0
	v_add_f32_e32 v0, 1.0, v0
	v_rcp_f32_e32 v0, v0
	s_nop 0
	v_fmac_f32_e32 v137, v105, v0
	v_or_b32_e32 v0, 32, v166
	v_cvt_pk_bf16_f32 v137, v150, v137
	global_store_dwordx4 v[146:147], v[134:137], off offset:256 nt
	s_nop 1
	v_mad_i64_i32 v[134:135], s[22:23], v0, s29, v[168:169]
	v_lshl_add_u64 v[134:135], v[134:135], 0, v[164:165]
	v_add_co_u32_e32 v136, vcc, s98, v134
	v_or_b32_e32 v0, 48, v166
	s_nop 0
	v_addc_co_u32_e32 v137, vcc, 0, v135, vcc
	global_load_dwordx4 v[154:157], v[136:137], off offset:3072 nt
	global_load_dwordx4 v[150:153], v[136:137], off offset:3328 nt
	global_load_dwordx4 v[158:161], v[134:135], off offset:2048 nt
	global_load_dwordx4 v[170:173], v[134:135], off offset:2304 nt
	v_mad_i64_i32 v[134:135], s[22:23], v0, s29, v[168:169]
	v_lshl_add_u64 v[134:135], v[134:135], 0, v[164:165]
	v_add_co_u32_e32 v136, vcc, s98, v134
	s_waitcnt vmcnt(0)
; __device__ __forceinline__ float sigmoidf_(float g) { return __builtin_amdgcn_rcpf(1.f + __expf(-g)); }
; __device__ __forceinline__ u32x4 pack8(const f32x4& a, const f32x4& b) { u32x4 w; w.x = cvt_pk_bf16(a[0], a[1]); w.y = cvt_pk_bf16(a[2], a[3]); w.z = cvt_pk_bf16(b[0], b[1]); w.w = cvt_pk_bf16(b[2], b[3]); return w; }
; __device__ __forceinline__ void unpack8(const u32x4& w, float (&v)[8]) { v[0] = bf_lo(w.x); v[1] = bf_hi(w.x); v[2] = bf_lo(w.y); v[3] = bf_hi(w.y); v[4] = bf_lo(w.z); v[5] = bf_hi(w.z); v[6] = bf_lo(w.w); v[7] = bf_hi(w.w); }
;     __device__ __forceinline__ void apply(const Ld& d, int row, int c0, int, int, int, const f32x4& a0, const f32x4& b0, const f32x4& a1, const f32x4& b1) const { half(d.g0, row, c0, a0, b0); half(d.g1, row, c0 + 128, a1, b1); }
;     __device__ __forceinline__ void half(const u32x4& gw, const u32x4& pw, int row, int col, const f32x4& a, const f32x4& b) const {
;         float g[8]; unpack8(gw, g); float p[8]; unpack8(pw, p);
;         f32x4 r0, r1;
; #pragma unroll
;         for (int i = 0; i < 4; ++i) { r0[i] = a[i] * sigmoidf_(g[i]) + p[i]; r1[i] = b[i] * sigmoidf_(g[4 + i]) + p[4 + i]; }
;         *(u32x4*)(merged + (size_t)row * 1024 + col) = pack8(r0, r1);
;     }
;     __device__ __forceinline__ void apply(const Ld& d, int row, int c0, int, int, int, const f32x4& a0, const f32x4& b0, const f32x4& a1, const f32x4& b1) const { half(d.g0, d.p0, row, c0, a0, b0); half(d.g1, d.p1, row, c0 + 128, a1, b1); }
	v_lshlrev_b32_e32 v0, 16, v154
	v_mul_f32_e32 v0, 0xbfb8aa3b, v0
	v_exp_f32_e32 v0, v0
	v_lshlrev_b32_e32 v175, 16, v156
	v_lshlrev_b32_e32 v177, 16, v158
	v_and_b32_e32 v154, 0xffff0000, v154
	v_add_f32_e32 v0, 1.0, v0
	v_rcp_f32_e32 v0, v0
	v_lshlrev_b32_e32 v179, 16, v160
	v_and_b32_e32 v156, 0xffff0000, v156
	v_and_b32_e32 v158, 0xffff0000, v158
	v_fmac_f32_e32 v177, v98, v0
	v_mul_f32_e32 v0, 0xbfb8aa3b, v175
	v_exp_f32_e32 v0, v0
	v_lshlrev_b32_e32 v167, 16, v155
	v_and_b32_e32 v160, 0xffff0000, v160
	v_lshlrev_b32_e32 v176, 16, v157
	v_add_f32_e32 v0, 1.0, v0
	v_rcp_f32_e32 v0, v0
	v_lshlrev_b32_e32 v178, 16, v159
	v_and_b32_e32 v155, 0xffff0000, v155
	v_lshlrev_b32_e32 v180, 16, v161
	v_fmac_f32_e32 v179, v94, v0
	v_mul_f32_e32 v0, 0xbfb8aa3b, v154
	v_exp_f32_e32 v0, v0
	v_and_b32_e32 v157, 0xffff0000, v157
	v_and_b32_e32 v159, 0xffff0000, v159
	v_and_b32_e32 v161, 0xffff0000, v161
	v_add_f32_e32 v0, 1.0, v0
	v_rcp_f32_e32 v0, v0
	v_addc_co_u32_e32 v137, vcc, 0, v135, vcc
	global_load_dwordx4 v[146:149], v[136:137], off offset:3072 nt
	global_load_dwordx4 v[138:141], v[136:137], off offset:3328 nt
	global_load_dwordx4 v[142:145], v[134:135], off offset:2048 nt
	s_nop 0
	global_load_dwordx4 v[134:137], v[134:135], off offset:2304 nt
	v_fmac_f32_e32 v158, v99, v0
	v_mul_f32_e32 v0, 0xbfb8aa3b, v156
	v_exp_f32_e32 v0, v0
	v_ashrrev_i32_e32 v175, 31, v174
	v_cvt_pk_bf16_f32 v154, v177, v158
	v_add_f32_e32 v0, 1.0, v0
	v_rcp_f32_e32 v0, v0
	s_nop 0
	v_fmac_f32_e32 v160, v95, v0
	v_mul_f32_e32 v0, 0xbfb8aa3b, v167
	v_exp_f32_e32 v0, v0
	v_and_b32_e32 v167, 0xffff0000, v171
	v_add_f32_e32 v0, 1.0, v0
	v_rcp_f32_e32 v0, v0
	s_nop 0
	v_fmac_f32_e32 v178, v100, v0
	v_mul_f32_e32 v0, 0xbfb8aa3b, v176
	v_exp_f32_e32 v0, v0
	s_nop 0
	v_add_f32_e32 v0, 1.0, v0
	v_rcp_f32_e32 v0, v0
	s_nop 0
	v_fmac_f32_e32 v180, v96, v0
	v_mul_f32_e32 v0, 0xbfb8aa3b, v155
	v_exp_f32_e32 v0, v0
	s_nop 0
	v_add_f32_e32 v0, 1.0, v0
	v_rcp_f32_e32 v0, v0
	s_nop 0
	v_fmac_f32_e32 v159, v101, v0
	v_mul_f32_e32 v0, 0xbfb8aa3b, v157
	v_exp_f32_e32 v0, v0
	v_cvt_pk_bf16_f32 v155, v178, v159
	v_lshlrev_b64 v[158:159], 11, v[174:175]
	v_cvt_pk_bf16_f32 v156, v179, v160
	v_add_f32_e32 v0, 1.0, v0
	v_rcp_f32_e32 v0, v0
	v_lshl_add_u64 v[158:159], v[162:163], 0, v[158:159]
	v_and_b32_e32 v160, 0xffff0000, v170
	v_fmac_f32_e32 v161, v97, v0
	v_lshlrev_b32_e32 v0, 16, v150
	v_mul_f32_e32 v0, 0xbfb8aa3b, v0
	v_exp_f32_e32 v0, v0
	v_cvt_pk_bf16_f32 v157, v180, v161
	global_store_dwordx4 v[158:159], v[154:157], off nt
	v_and_b32_e32 v150, 0xffff0000, v150
	v_add_f32_e32 v0, 1.0, v0
	v_rcp_f32_e32 v0, v0
	v_lshlrev_b32_e32 v155, 16, v152
	v_lshlrev_b32_e32 v157, 16, v170
	v_lshlrev_b32_e32 v170, 16, v172
	v_fmac_f32_e32 v157, v90, v0
	v_mul_f32_e32 v0, 0xbfb8aa3b, v155
	v_exp_f32_e32 v0, v0
	v_and_b32_e32 v152, 0xffff0000, v152
	v_lshlrev_b32_e32 v154, 16, v151
	v_lshlrev_b32_e32 v161, 16, v171
	v_add_f32_e32 v0, 1.0, v0
	v_rcp_f32_e32 v0, v0
	v_and_b32_e32 v171, 0xffff0000, v172
	v_lshlrev_b32_e32 v156, 16, v153
	v_and_b32_e32 v151, 0xffff0000, v151
	v_fmac_f32_e32 v170, v86, v0
	v_mul_f32_e32 v0, 0xbfb8aa3b, v150
	v_exp_f32_e32 v0, v0
	v_lshlrev_b32_e32 v172, 16, v173
	v_and_b32_e32 v153, 0xffff0000, v153
	v_and_b32_e32 v173, 0xffff0000, v173
	v_add_f32_e32 v0, 1.0, v0
	v_rcp_f32_e32 v0, v0
	s_waitcnt vmcnt(1)
	v_lshlrev_b32_e32 v155, 16, v143
	v_and_b32_e32 v143, 0xffff0000, v143
	v_fmac_f32_e32 v160, v91, v0
	v_mul_f32_e32 v0, 0xbfb8aa3b, v152
	v_exp_f32_e32 v0, v0
	v_cvt_pk_bf16_f32 v150, v157, v160
	v_lshlrev_b32_e32 v157, 16, v145
	v_and_b32_e32 v145, 0xffff0000, v145
	v_add_f32_e32 v0, 1.0, v0
	v_rcp_f32_e32 v0, v0
	s_nop 0
	v_fmac_f32_e32 v171, v87, v0
	v_mul_f32_e32 v0, 0xbfb8aa3b, v154
	v_exp_f32_e32 v0, v0
	v_lshlrev_b32_e32 v154, 16, v142
	v_and_b32_e32 v142, 0xffff0000, v142
	v_add_f32_e32 v0, 1.0, v0
	v_rcp_f32_e32 v0, v0
	s_nop 0
	v_fmac_f32_e32 v161, v92, v0
	v_mul_f32_e32 v0, 0xbfb8aa3b, v156
	v_exp_f32_e32 v0, v0
	v_lshlrev_b32_e32 v156, 16, v144
	v_and_b32_e32 v144, 0xffff0000, v144
	v_add_f32_e32 v0, 1.0, v0
	v_rcp_f32_e32 v0, v0
	s_nop 0
	v_fmac_f32_e32 v172, v88, v0
	v_mul_f32_e32 v0, 0xbfb8aa3b, v151
	v_exp_f32_e32 v0, v0
	s_nop 0
	v_add_f32_e32 v0, 1.0, v0
	v_rcp_f32_e32 v0, v0
	s_nop 0
	v_fmac_f32_e32 v167, v93, v0
	v_mul_f32_e32 v0, 0xbfb8aa3b, v153
	v_exp_f32_e32 v0, v0
	v_cvt_pk_bf16_f32 v151, v161, v167
	v_cvt_pk_bf16_f32 v152, v170, v171
	s_nop 0
	v_add_f32_e32 v0, 1.0, v0
	v_rcp_f32_e32 v0, v0
	s_nop 0
	v_fmac_f32_e32 v173, v89, v0
	v_lshlrev_b32_e32 v0, 16, v146
	v_mul_f32_e32 v0, 0xbfb8aa3b, v0
	v_exp_f32_e32 v0, v0
	v_cvt_pk_bf16_f32 v153, v172, v173
	global_store_dwordx4 v[158:159], v[150:153], off offset:256 nt
	v_and_b32_e32 v146, 0xffff0000, v146
	v_add_f32_e32 v0, 1.0, v0
	v_rcp_f32_e32 v0, v0
	v_lshlrev_b32_e32 v152, 16, v148
	v_and_b32_e32 v148, 0xffff0000, v148
	v_lshlrev_b32_e32 v151, 16, v147
	v_fmac_f32_e32 v154, v82, v0
	v_mul_f32_e32 v0, 0xbfb8aa3b, v152
	v_exp_f32_e32 v0, v0
	v_lshlrev_b32_e32 v153, 16, v149
	v_and_b32_e32 v147, 0xffff0000, v147
	v_and_b32_e32 v149, 0xffff0000, v149
	v_add_f32_e32 v0, 1.0, v0
	v_rcp_f32_e32 v0, v0
	v_add_u32_e32 v150, s0, v237
	v_fmac_f32_e32 v156, v78, v0
	v_mul_f32_e32 v0, 0xbfb8aa3b, v146
	v_exp_f32_e32 v0, v0
	s_nop 0
	v_add_f32_e32 v0, 1.0, v0
	v_rcp_f32_e32 v0, v0
	s_nop 0
	v_fmac_f32_e32 v142, v83, v0
	v_mul_f32_e32 v0, 0xbfb8aa3b, v148
	v_exp_f32_e32 v0, v0
	v_cvt_pk_bf16_f32 v142, v154, v142
	v_lshlrev_b32_e32 v148, 16, v135
	v_and_b32_e32 v135, 0xffff0000, v135
	v_add_f32_e32 v0, 1.0, v0
	v_rcp_f32_e32 v0, v0
	v_add_u32_e32 v154, 0x80, v166
	v_fmac_f32_e32 v144, v79, v0
; __device__ __forceinline__ float sigmoidf_(float g) { return __builtin_amdgcn_rcpf(1.f + __expf(-g)); }
; __device__ __forceinline__ u32x4 pack8(const f32x4& a, const f32x4& b) { u32x4 w; w.x = cvt_pk_bf16(a[0], a[1]); w.y = cvt_pk_bf16(a[2], a[3]); w.z = cvt_pk_bf16(b[0], b[1]); w.w = cvt_pk_bf16(b[2], b[3]); return w; }
; __device__ __forceinline__ void unpack8(const u32x4& w, float (&v)[8]) { v[0] = bf_lo(w.x); v[1] = bf_hi(w.x); v[2] = bf_lo(w.y); v[3] = bf_hi(w.y); v[4] = bf_lo(w.z); v[5] = bf_hi(w.z); v[6] = bf_lo(w.w); v[7] = bf_hi(w.w); }
;     __device__ __forceinline__ void apply(const Ld& d, int row, int c0, int, int, int, const f32x4& a0, const f32x4& b0, const f32x4& a1, const f32x4& b1) const { half(d.g0, row, c0, a0, b0); half(d.g1, row, c0 + 128, a1, b1); }
;     __device__ __forceinline__ void half(const u32x4& gw, const u32x4& pw, int row, int col, const f32x4& a, const f32x4& b) const {
;         float g[8]; unpack8(gw, g); float p[8]; unpack8(pw, p);
;         f32x4 r0, r1;
; #pragma unroll
;         for (int i = 0; i < 4; ++i) { r0[i] = a[i] * sigmoidf_(g[i]) + p[i]; r1[i] = b[i] * sigmoidf_(g[4 + i]) + p[4 + i]; }
;         *(u32x4*)(merged + (size_t)row * 1024 + col) = pack8(r0, r1);
;     }
;     __device__ __forceinline__ void apply(const Ld& d, int row, int c0, int, int, int, const f32x4& a0, const f32x4& b0, const f32x4& a1, const f32x4& b1) const { half(d.g0, d.p0, row, c0, a0, b0); half(d.g1, d.p1, row, c0 + 128, a1, b1); }
	v_mul_f32_e32 v0, 0xbfb8aa3b, v151
	v_exp_f32_e32 v0, v0
	v_ashrrev_i32_e32 v151, 31, v150
	v_add_f32_e32 v0, 1.0, v0
	v_rcp_f32_e32 v0, v0
	s_nop 0
	v_fmac_f32_e32 v155, v84, v0
	v_mul_f32_e32 v0, 0xbfb8aa3b, v153
	v_exp_f32_e32 v0, v0
	s_nop 0
	v_add_f32_e32 v0, 1.0, v0
	v_rcp_f32_e32 v0, v0
	s_nop 0
	v_fmac_f32_e32 v157, v80, v0
	v_mul_f32_e32 v0, 0xbfb8aa3b, v147
	v_exp_f32_e32 v0, v0
	v_lshlrev_b64 v[146:147], 11, v[150:151]
	v_lshl_add_u64 v[146:147], v[162:163], 0, v[146:147]
	v_lshlrev_b32_e32 v150, 16, v137
	v_add_f32_e32 v0, 1.0, v0
	v_rcp_f32_e32 v0, v0
	v_and_b32_e32 v137, 0xffff0000, v137
	v_fmac_f32_e32 v143, v85, v0
	v_mul_f32_e32 v0, 0xbfb8aa3b, v149
	v_exp_f32_e32 v0, v0
	v_cvt_pk_bf16_f32 v143, v155, v143
	v_cvt_pk_bf16_f32 v144, v156, v144
	v_lshlrev_b32_e32 v149, 16, v136
	v_add_f32_e32 v0, 1.0, v0
	v_rcp_f32_e32 v0, v0
	v_and_b32_e32 v136, 0xffff0000, v136
	v_ashrrev_i32_e32 v155, 31, v154
	v_fmac_f32_e32 v145, v81, v0
	v_lshlrev_b32_e32 v0, 16, v138
	v_mul_f32_e32 v0, 0xbfb8aa3b, v0
	v_exp_f32_e32 v0, v0
	v_cvt_pk_bf16_f32 v145, v157, v145
	global_store_dwordx4 v[146:147], v[142:145], off nt
	v_and_b32_e32 v138, 0xffff0000, v138
	v_add_f32_e32 v0, 1.0, v0
	v_rcp_f32_e32 v0, v0
	v_lshlrev_b32_e32 v143, 16, v140
	v_lshlrev_b32_e32 v145, 16, v134
	v_and_b32_e32 v140, 0xffff0000, v140
	v_fmac_f32_e32 v145, v74, v0
	v_mul_f32_e32 v0, 0xbfb8aa3b, v143
	v_exp_f32_e32 v0, v0
	v_and_b32_e32 v134, 0xffff0000, v134
	v_lshlrev_b32_e32 v142, 16, v139
	v_lshlrev_b32_e32 v144, 16, v141
	v_add_f32_e32 v0, 1.0, v0
	v_rcp_f32_e32 v0, v0
	v_and_b32_e32 v139, 0xffff0000, v139
	v_and_b32_e32 v141, 0xffff0000, v141
	v_fmac_f32_e32 v149, v70, v0
	v_mul_f32_e32 v0, 0xbfb8aa3b, v138
	v_exp_f32_e32 v0, v0
	s_nop 0
	v_add_f32_e32 v0, 1.0, v0
	v_rcp_f32_e32 v0, v0
	s_nop 0
	v_fmac_f32_e32 v134, v75, v0
	v_mul_f32_e32 v0, 0xbfb8aa3b, v140
	v_exp_f32_e32 v0, v0
	v_cvt_pk_bf16_f32 v134, v145, v134
	s_nop 0
	v_add_f32_e32 v0, 1.0, v0
	v_rcp_f32_e32 v0, v0
	s_nop 0
	v_fmac_f32_e32 v136, v71, v0
	v_mul_f32_e32 v0, 0xbfb8aa3b, v142
	v_exp_f32_e32 v0, v0
	s_nop 0
	v_add_f32_e32 v0, 1.0, v0
	v_rcp_f32_e32 v0, v0
	s_nop 0
	v_fmac_f32_e32 v148, v76, v0
	v_mul_f32_e32 v0, 0xbfb8aa3b, v144
	v_exp_f32_e32 v0, v0
	s_nop 0
	v_add_f32_e32 v0, 1.0, v0
	v_rcp_f32_e32 v0, v0
	s_nop 0
	v_fmac_f32_e32 v150, v72, v0
	v_mul_f32_e32 v0, 0xbfb8aa3b, v139
	v_exp_f32_e32 v0, v0
	s_nop 0
	v_add_f32_e32 v0, 1.0, v0
	v_rcp_f32_e32 v0, v0
	s_nop 0
	v_fmac_f32_e32 v135, v77, v0
	v_mul_f32_e32 v0, 0xbfb8aa3b, v141
	v_exp_f32_e32 v0, v0
	v_cvt_pk_bf16_f32 v135, v148, v135
	v_cvt_pk_bf16_f32 v136, v149, v136
	s_nop 0
	v_add_f32_e32 v0, 1.0, v0
	v_rcp_f32_e32 v0, v0
	s_nop 0
	v_fmac_f32_e32 v137, v73, v0
	v_cvt_pk_bf16_f32 v137, v150, v137
	global_store_dwordx4 v[146:147], v[134:137], off offset:256 nt
	v_add_u32_e32 v0, 0x90, v166
	s_nop 0
	v_mad_i64_i32 v[134:135], s[22:23], v154, s29, v[168:169]
	v_lshl_add_u64 v[134:135], v[134:135], 0, v[164:165]
	v_add_co_u32_e32 v136, vcc, s98, v134
	v_lshlrev_b64 v[154:155], 11, v[154:155]
	s_nop 0
	v_addc_co_u32_e32 v137, vcc, 0, v135, vcc
	global_load_dwordx4 v[156:159], v[136:137], off offset:3072 nt
	global_load_dwordx4 v[150:153], v[136:137], off offset:3328 nt
	global_load_dwordx4 v[170:173], v[134:135], off offset:2048 nt
	global_load_dwordx4 v[174:177], v[134:135], off offset:2304 nt
	v_mad_i64_i32 v[134:135], s[22:23], v0, s29, v[168:169]
	v_lshl_add_u64 v[134:135], v[134:135], 0, v[164:165]
	v_add_co_u32_e32 v136, vcc, s98, v134
	v_lshl_add_u64 v[154:155], v[162:163], 0, v[154:155]
	s_nop 0
	v_addc_co_u32_e32 v137, vcc, 0, v135, vcc
	global_load_dwordx4 v[146:149], v[136:137], off offset:3072 nt
	global_load_dwordx4 v[138:141], v[136:137], off offset:3328 nt
	global_load_dwordx4 v[142:145], v[134:135], off offset:2048 nt
	s_nop 0
	global_load_dwordx4 v[134:137], v[134:135], off offset:2304 nt
	s_waitcnt vmcnt(0)
	v_lshlrev_b32_e32 v0, 16, v156
	v_mul_f32_e32 v0, 0xbfb8aa3b, v0
	v_exp_f32_e32 v0, v0
	v_lshlrev_b32_e32 v161, 16, v158
	v_lshlrev_b32_e32 v178, 16, v170
	v_and_b32_e32 v156, 0xffff0000, v156
	v_add_f32_e32 v0, 1.0, v0
	v_rcp_f32_e32 v0, v0
	v_lshlrev_b32_e32 v180, 16, v172
	v_and_b32_e32 v158, 0xffff0000, v158
	v_and_b32_e32 v170, 0xffff0000, v170
	v_fmac_f32_e32 v178, v66, v0
	v_mul_f32_e32 v0, 0xbfb8aa3b, v161
	v_exp_f32_e32 v0, v0
	v_lshlrev_b32_e32 v160, 16, v157
	v_and_b32_e32 v172, 0xffff0000, v172
	v_lshlrev_b32_e32 v167, 16, v159
	v_add_f32_e32 v0, 1.0, v0
	v_rcp_f32_e32 v0, v0
	v_lshlrev_b32_e32 v179, 16, v171
	v_and_b32_e32 v157, 0xffff0000, v157
	v_lshlrev_b32_e32 v181, 16, v173
	v_fmac_f32_e32 v180, v62, v0
	v_mul_f32_e32 v0, 0xbfb8aa3b, v156
	v_exp_f32_e32 v0, v0
	v_and_b32_e32 v159, 0xffff0000, v159
	v_and_b32_e32 v171, 0xffff0000, v171
	v_and_b32_e32 v173, 0xffff0000, v173
	v_add_f32_e32 v0, 1.0, v0
	v_rcp_f32_e32 v0, v0
	v_lshlrev_b32_e32 v161, 16, v175
	v_fmac_f32_e32 v170, v67, v0
	v_mul_f32_e32 v0, 0xbfb8aa3b, v158
	v_exp_f32_e32 v0, v0
	v_cvt_pk_bf16_f32 v156, v178, v170
	v_lshlrev_b32_e32 v170, 16, v176
	v_add_f32_e32 v0, 1.0, v0
	v_rcp_f32_e32 v0, v0
	s_nop 0
	v_fmac_f32_e32 v172, v63, v0
	v_mul_f32_e32 v0, 0xbfb8aa3b, v160
	v_exp_f32_e32 v0, v0
	v_and_b32_e32 v160, 0xffff0000, v174
	v_add_f32_e32 v0, 1.0, v0
	v_rcp_f32_e32 v0, v0
	s_nop 0
	v_fmac_f32_e32 v179, v68, v0
	v_mul_f32_e32 v0, 0xbfb8aa3b, v167
	v_exp_f32_e32 v0, v0
	v_and_b32_e32 v167, 0xffff0000, v175
	v_add_f32_e32 v0, 1.0, v0
	v_rcp_f32_e32 v0, v0
	s_nop 0
	v_fmac_f32_e32 v181, v64, v0
	v_mul_f32_e32 v0, 0xbfb8aa3b, v157
	v_exp_f32_e32 v0, v0
	s_nop 0
	v_add_f32_e32 v0, 1.0, v0
	v_rcp_f32_e32 v0, v0
	s_nop 0
	v_fmac_f32_e32 v171, v69, v0
; __device__ __forceinline__ float sigmoidf_(float g) { return __builtin_amdgcn_rcpf(1.f + __expf(-g)); }
; __device__ __forceinline__ u32x4 pack8(const f32x4& a, const f32x4& b) { u32x4 w; w.x = cvt_pk_bf16(a[0], a[1]); w.y = cvt_pk_bf16(a[2], a[3]); w.z = cvt_pk_bf16(b[0], b[1]); w.w = cvt_pk_bf16(b[2], b[3]); return w; }
; __device__ __forceinline__ void unpack8(const u32x4& w, float (&v)[8]) { v[0] = bf_lo(w.x); v[1] = bf_hi(w.x); v[2] = bf_lo(w.y); v[3] = bf_hi(w.y); v[4] = bf_lo(w.z); v[5] = bf_hi(w.z); v[6] = bf_lo(w.w); v[7] = bf_hi(w.w); }
;     __device__ __forceinline__ void apply(const Ld& d, int row, int c0, int, int, int, const f32x4& a0, const f32x4& b0, const f32x4& a1, const f32x4& b1) const { half(d.g0, row, c0, a0, b0); half(d.g1, row, c0 + 128, a1, b1); }
;     __device__ __forceinline__ void half(const u32x4& gw, const u32x4& pw, int row, int col, const f32x4& a, const f32x4& b) const {
;         float g[8]; unpack8(gw, g); float p[8]; unpack8(pw, p);
;         f32x4 r0, r1;
; #pragma unroll
;         for (int i = 0; i < 4; ++i) { r0[i] = a[i] * sigmoidf_(g[i]) + p[i]; r1[i] = b[i] * sigmoidf_(g[4 + i]) + p[4 + i]; }
;         *(u32x4*)(merged + (size_t)row * 1024 + col) = pack8(r0, r1);
;     }
;     __device__ __forceinline__ void apply(const Ld& d, int row, int c0, int, int, int, const f32x4& a0, const f32x4& b0, const f32x4& a1, const f32x4& b1) const { half(d.g0, d.p0, row, c0, a0, b0); half(d.g1, d.p1, row, c0 + 128, a1, b1); }
	v_mul_f32_e32 v0, 0xbfb8aa3b, v159
	v_exp_f32_e32 v0, v0
	v_cvt_pk_bf16_f32 v157, v179, v171
	v_cvt_pk_bf16_f32 v158, v180, v172
	v_and_b32_e32 v171, 0xffff0000, v176
	v_add_f32_e32 v0, 1.0, v0
	v_rcp_f32_e32 v0, v0
	v_lshlrev_b32_e32 v172, 16, v177
	v_fmac_f32_e32 v173, v65, v0
	v_lshlrev_b32_e32 v0, 16, v150
	v_mul_f32_e32 v0, 0xbfb8aa3b, v0
	v_exp_f32_e32 v0, v0
	v_cvt_pk_bf16_f32 v159, v181, v173
	global_store_dwordx4 v[154:155], v[156:159], off nt
	v_and_b32_e32 v150, 0xffff0000, v150
	v_add_f32_e32 v0, 1.0, v0
	v_rcp_f32_e32 v0, v0
	v_lshlrev_b32_e32 v157, 16, v152
	v_lshlrev_b32_e32 v159, 16, v174
	v_and_b32_e32 v152, 0xffff0000, v152
	v_fmac_f32_e32 v159, v58, v0
	v_mul_f32_e32 v0, 0xbfb8aa3b, v157
	v_exp_f32_e32 v0, v0
	v_lshlrev_b32_e32 v156, 16, v151
	v_lshlrev_b32_e32 v158, 16, v153
	v_and_b32_e32 v151, 0xffff0000, v151
	v_add_f32_e32 v0, 1.0, v0
	v_rcp_f32_e32 v0, v0
	v_and_b32_e32 v153, 0xffff0000, v153
	v_and_b32_e32 v173, 0xffff0000, v177
	v_lshlrev_b32_e32 v157, 16, v145
	v_fmac_f32_e32 v170, v54, v0
	v_mul_f32_e32 v0, 0xbfb8aa3b, v150
	v_exp_f32_e32 v0, v0
	v_and_b32_e32 v145, 0xffff0000, v145
	v_add_f32_e32 v0, 1.0, v0
	v_rcp_f32_e32 v0, v0
	s_nop 0
	v_fmac_f32_e32 v160, v59, v0
	v_mul_f32_e32 v0, 0xbfb8aa3b, v152
	v_exp_f32_e32 v0, v0
	v_cvt_pk_bf16_f32 v150, v159, v160
	s_nop 0
	v_add_f32_e32 v0, 1.0, v0
	v_rcp_f32_e32 v0, v0
	s_nop 0
	v_fmac_f32_e32 v171, v55, v0
	v_mul_f32_e32 v0, 0xbfb8aa3b, v156
	v_exp_f32_e32 v0, v0
	v_lshlrev_b32_e32 v156, 16, v144
	v_and_b32_e32 v144, 0xffff0000, v144
	v_add_f32_e32 v0, 1.0, v0
	v_rcp_f32_e32 v0, v0
	s_nop 0
	v_fmac_f32_e32 v161, v60, v0
	v_mul_f32_e32 v0, 0xbfb8aa3b, v158
	v_exp_f32_e32 v0, v0
	s_nop 0
	v_add_f32_e32 v0, 1.0, v0
	v_rcp_f32_e32 v0, v0
	s_nop 0
	v_fmac_f32_e32 v172, v56, v0
	v_mul_f32_e32 v0, 0xbfb8aa3b, v151
	v_exp_f32_e32 v0, v0
	s_nop 0
	v_add_f32_e32 v0, 1.0, v0
	v_rcp_f32_e32 v0, v0
	s_nop 0
	v_fmac_f32_e32 v167, v61, v0
	v_mul_f32_e32 v0, 0xbfb8aa3b, v153
	v_exp_f32_e32 v0, v0
	v_cvt_pk_bf16_f32 v151, v161, v167
	v_cvt_pk_bf16_f32 v152, v170, v171
	s_nop 0
	v_add_f32_e32 v0, 1.0, v0
	v_rcp_f32_e32 v0, v0
	s_nop 0
	v_fmac_f32_e32 v173, v57, v0
	v_lshlrev_b32_e32 v0, 16, v146
	v_mul_f32_e32 v0, 0xbfb8aa3b, v0
	v_exp_f32_e32 v0, v0
	v_cvt_pk_bf16_f32 v153, v172, v173
	global_store_dwordx4 v[154:155], v[150:153], off offset:256 nt
	v_lshlrev_b32_e32 v154, 16, v142
	v_add_f32_e32 v0, 1.0, v0
	v_rcp_f32_e32 v0, v0
	v_lshlrev_b32_e32 v152, 16, v148
	v_and_b32_e32 v146, 0xffff0000, v146
	v_and_b32_e32 v148, 0xffff0000, v148
	v_fmac_f32_e32 v154, v50, v0
	v_mul_f32_e32 v0, 0xbfb8aa3b, v152
	v_exp_f32_e32 v0, v0
	v_and_b32_e32 v142, 0xffff0000, v142
	v_lshlrev_b32_e32 v151, 16, v147
	v_lshlrev_b32_e32 v153, 16, v149
	v_add_f32_e32 v0, 1.0, v0
	v_rcp_f32_e32 v0, v0
	v_lshlrev_b32_e32 v155, 16, v143
	v_and_b32_e32 v147, 0xffff0000, v147
	v_and_b32_e32 v149, 0xffff0000, v149
	v_fmac_f32_e32 v156, v46, v0
	v_mul_f32_e32 v0, 0xbfb8aa3b, v146
	v_exp_f32_e32 v0, v0
	v_and_b32_e32 v143, 0xffff0000, v143
	v_add_u32_e32 v150, s0, v238
	v_add_f32_e32 v0, 1.0, v0
	v_rcp_f32_e32 v0, v0
	s_nop 0
	v_fmac_f32_e32 v142, v51, v0
	v_mul_f32_e32 v0, 0xbfb8aa3b, v148
	v_exp_f32_e32 v0, v0
	v_cvt_pk_bf16_f32 v142, v154, v142
	v_lshlrev_b32_e32 v148, 16, v135
	v_and_b32_e32 v135, 0xffff0000, v135
	v_add_f32_e32 v0, 1.0, v0
	v_rcp_f32_e32 v0, v0
	s_nop 0
	v_fmac_f32_e32 v144, v47, v0
	v_mul_f32_e32 v0, 0xbfb8aa3b, v151
	v_exp_f32_e32 v0, v0
	v_ashrrev_i32_e32 v151, 31, v150
	v_add_f32_e32 v0, 1.0, v0
	v_rcp_f32_e32 v0, v0
	s_nop 0
	v_fmac_f32_e32 v155, v52, v0
	v_mul_f32_e32 v0, 0xbfb8aa3b, v153
	v_exp_f32_e32 v0, v0
	s_nop 0
	v_add_f32_e32 v0, 1.0, v0
	v_rcp_f32_e32 v0, v0
	s_nop 0
	v_fmac_f32_e32 v157, v48, v0
	v_mul_f32_e32 v0, 0xbfb8aa3b, v147
	v_exp_f32_e32 v0, v0
	v_lshlrev_b64 v[146:147], 11, v[150:151]
	v_lshl_add_u64 v[146:147], v[162:163], 0, v[146:147]
	v_lshlrev_b32_e32 v150, 16, v137
	v_add_f32_e32 v0, 1.0, v0
	v_rcp_f32_e32 v0, v0
	v_and_b32_e32 v137, 0xffff0000, v137
	v_fmac_f32_e32 v143, v53, v0
	v_mul_f32_e32 v0, 0xbfb8aa3b, v149
	v_exp_f32_e32 v0, v0
	v_cvt_pk_bf16_f32 v143, v155, v143
	v_cvt_pk_bf16_f32 v144, v156, v144
	v_lshlrev_b32_e32 v149, 16, v136
	v_add_f32_e32 v0, 1.0, v0
	v_rcp_f32_e32 v0, v0
	v_and_b32_e32 v136, 0xffff0000, v136
	v_fmac_f32_e32 v145, v49, v0
	v_lshlrev_b32_e32 v0, 16, v138
	v_mul_f32_e32 v0, 0xbfb8aa3b, v0
	v_exp_f32_e32 v0, v0
	v_cvt_pk_bf16_f32 v145, v157, v145
	global_store_dwordx4 v[146:147], v[142:145], off nt
	v_and_b32_e32 v138, 0xffff0000, v138
	v_add_f32_e32 v0, 1.0, v0
	v_rcp_f32_e32 v0, v0
	v_lshlrev_b32_e32 v143, 16, v140
	v_lshlrev_b32_e32 v145, 16, v134
	v_and_b32_e32 v140, 0xffff0000, v140
	v_fmac_f32_e32 v145, v42, v0
	v_mul_f32_e32 v0, 0xbfb8aa3b, v143
	v_exp_f32_e32 v0, v0
	v_and_b32_e32 v134, 0xffff0000, v134
	v_lshlrev_b32_e32 v142, 16, v139
	v_lshlrev_b32_e32 v144, 16, v141
	v_add_f32_e32 v0, 1.0, v0
	v_rcp_f32_e32 v0, v0
	v_and_b32_e32 v139, 0xffff0000, v139
	v_and_b32_e32 v141, 0xffff0000, v141
	v_fmac_f32_e32 v149, v38, v0
	v_mul_f32_e32 v0, 0xbfb8aa3b, v138
	v_exp_f32_e32 v0, v0
	s_nop 0
	v_add_f32_e32 v0, 1.0, v0
	v_rcp_f32_e32 v0, v0
	s_nop 0
	v_fmac_f32_e32 v134, v43, v0
	v_mul_f32_e32 v0, 0xbfb8aa3b, v140
	v_exp_f32_e32 v0, v0
	v_cvt_pk_bf16_f32 v134, v145, v134
	s_nop 0
	v_add_f32_e32 v0, 1.0, v0
	v_rcp_f32_e32 v0, v0
	s_nop 0
	v_fmac_f32_e32 v136, v39, v0
	v_mul_f32_e32 v0, 0xbfb8aa3b, v142
	v_exp_f32_e32 v0, v0
	s_nop 0
	v_add_f32_e32 v0, 1.0, v0
	v_rcp_f32_e32 v0, v0
	s_nop 0
	v_fmac_f32_e32 v148, v44, v0
	v_mul_f32_e32 v0, 0xbfb8aa3b, v144
	v_exp_f32_e32 v0, v0
	s_nop 0
	v_add_f32_e32 v0, 1.0, v0
; __device__ __forceinline__ float sigmoidf_(float g) { return __builtin_amdgcn_rcpf(1.f + __expf(-g)); }
; __device__ __forceinline__ u32x4 pack8(const f32x4& a, const f32x4& b) { u32x4 w; w.x = cvt_pk_bf16(a[0], a[1]); w.y = cvt_pk_bf16(a[2], a[3]); w.z = cvt_pk_bf16(b[0], b[1]); w.w = cvt_pk_bf16(b[2], b[3]); return w; }
; __device__ __forceinline__ void unpack8(const u32x4& w, float (&v)[8]) { v[0] = bf_lo(w.x); v[1] = bf_hi(w.x); v[2] = bf_lo(w.y); v[3] = bf_hi(w.y); v[4] = bf_lo(w.z); v[5] = bf_hi(w.z); v[6] = bf_lo(w.w); v[7] = bf_hi(w.w); }
;     __device__ __forceinline__ void apply(const Ld& d, int row, int c0, int, int, int, const f32x4& a0, const f32x4& b0, const f32x4& a1, const f32x4& b1) const { half(d.g0, row, c0, a0, b0); half(d.g1, row, c0 + 128, a1, b1); }
;     __device__ __forceinline__ void half(const u32x4& gw, const u32x4& pw, int row, int col, const f32x4& a, const f32x4& b) const {
;         float g[8]; unpack8(gw, g); float p[8]; unpack8(pw, p);
;         f32x4 r0, r1;
; #pragma unroll
;         for (int i = 0; i < 4; ++i) { r0[i] = a[i] * sigmoidf_(g[i]) + p[i]; r1[i] = b[i] * sigmoidf_(g[4 + i]) + p[4 + i]; }
;         *(u32x4*)(merged + (size_t)row * 1024 + col) = pack8(r0, r1);
;     }
;     __device__ __forceinline__ void apply(const Ld& d, int row, int c0, int, int, int, const f32x4& a0, const f32x4& b0, const f32x4& a1, const f32x4& b1) const { half(d.g0, d.p0, row, c0, a0, b0); half(d.g1, d.p1, row, c0 + 128, a1, b1); }
	v_rcp_f32_e32 v0, v0
	s_nop 0
	v_fmac_f32_e32 v150, v40, v0
	v_mul_f32_e32 v0, 0xbfb8aa3b, v139
	v_exp_f32_e32 v0, v0
	s_nop 0
	v_add_f32_e32 v0, 1.0, v0
	v_rcp_f32_e32 v0, v0
	s_nop 0
	v_fmac_f32_e32 v135, v45, v0
	v_mul_f32_e32 v0, 0xbfb8aa3b, v141
	v_exp_f32_e32 v0, v0
	v_cvt_pk_bf16_f32 v135, v148, v135
	v_cvt_pk_bf16_f32 v136, v149, v136
	s_nop 0
	v_add_f32_e32 v0, 1.0, v0
	v_rcp_f32_e32 v0, v0
	s_nop 0
	v_fmac_f32_e32 v137, v41, v0
	v_add_u32_e32 v0, 0xa0, v166
	v_cvt_pk_bf16_f32 v137, v150, v137
	global_store_dwordx4 v[146:147], v[134:137], off offset:256 nt
	s_nop 1
	v_mad_i64_i32 v[134:135], s[22:23], v0, s29, v[168:169]
	v_lshl_add_u64 v[134:135], v[134:135], 0, v[164:165]
	v_add_co_u32_e32 v136, vcc, s98, v134
	v_add_u32_e32 v0, 0xb0, v166
	s_nop 0
	v_addc_co_u32_e32 v137, vcc, 0, v135, vcc
	global_load_dwordx4 v[154:157], v[136:137], off offset:3072 nt
	global_load_dwordx4 v[150:153], v[136:137], off offset:3328 nt
	global_load_dwordx4 v[158:161], v[134:135], off offset:2048 nt
	global_load_dwordx4 v[170:173], v[134:135], off offset:2304 nt
	v_mad_i64_i32 v[134:135], s[22:23], v0, s29, v[168:169]
	v_lshl_add_u64 v[134:135], v[134:135], 0, v[164:165]
	v_add_co_u32_e32 v136, vcc, s98, v134
	v_add_u32_e32 v164, s0, v239
	s_nop 0
	v_addc_co_u32_e32 v137, vcc, 0, v135, vcc
	global_load_dwordx4 v[146:149], v[136:137], off offset:3072 nt
	global_load_dwordx4 v[138:141], v[136:137], off offset:3328 nt
	global_load_dwordx4 v[142:145], v[134:135], off offset:2048 nt
	s_nop 0
	global_load_dwordx4 v[134:137], v[134:135], off offset:2304 nt
	s_waitcnt vmcnt(0)
	v_lshlrev_b32_e32 v0, 16, v154
	v_mul_f32_e32 v0, 0xbfb8aa3b, v0
	v_exp_f32_e32 v0, v0
	v_lshlrev_b32_e32 v166, 16, v156
	v_lshlrev_b32_e32 v168, 16, v158
	v_and_b32_e32 v154, 0xffff0000, v154
	v_add_f32_e32 v0, 1.0, v0
	v_rcp_f32_e32 v0, v0
	v_lshlrev_b32_e32 v174, 16, v160
	v_and_b32_e32 v156, 0xffff0000, v156
	v_and_b32_e32 v158, 0xffff0000, v158
	v_fmac_f32_e32 v168, v34, v0
	v_mul_f32_e32 v0, 0xbfb8aa3b, v166
	v_exp_f32_e32 v0, v0
	v_lshlrev_b32_e32 v165, 16, v155
	v_and_b32_e32 v160, 0xffff0000, v160
	v_lshlrev_b32_e32 v167, 16, v157
	v_add_f32_e32 v0, 1.0, v0
	v_rcp_f32_e32 v0, v0
	v_lshlrev_b32_e32 v169, 16, v159
	v_and_b32_e32 v155, 0xffff0000, v155
	v_lshlrev_b32_e32 v175, 16, v161
	v_fmac_f32_e32 v174, v30, v0
	v_mul_f32_e32 v0, 0xbfb8aa3b, v154
	v_exp_f32_e32 v0, v0
	v_and_b32_e32 v157, 0xffff0000, v157
	v_and_b32_e32 v159, 0xffff0000, v159
	v_and_b32_e32 v161, 0xffff0000, v161
	v_add_f32_e32 v0, 1.0, v0
	v_rcp_f32_e32 v0, v0
	v_and_b32_e32 v166, 0xffff0000, v172
	v_fmac_f32_e32 v158, v35, v0
	v_mul_f32_e32 v0, 0xbfb8aa3b, v156
	v_exp_f32_e32 v0, v0
	v_cvt_pk_bf16_f32 v154, v168, v158
	v_and_b32_e32 v168, 0xffff0000, v173
	v_add_f32_e32 v0, 1.0, v0
	v_rcp_f32_e32 v0, v0
	s_nop 0
	v_fmac_f32_e32 v160, v31, v0
	v_mul_f32_e32 v0, 0xbfb8aa3b, v165
	v_exp_f32_e32 v0, v0
	v_ashrrev_i32_e32 v165, 31, v164
	v_add_f32_e32 v0, 1.0, v0
	v_rcp_f32_e32 v0, v0
	s_nop 0
	v_fmac_f32_e32 v169, v36, v0
	v_mul_f32_e32 v0, 0xbfb8aa3b, v167
	v_exp_f32_e32 v0, v0
	v_lshlrev_b32_e32 v167, 16, v173
	v_add_f32_e32 v0, 1.0, v0
	v_rcp_f32_e32 v0, v0
	s_nop 0
	v_fmac_f32_e32 v175, v32, v0
	v_mul_f32_e32 v0, 0xbfb8aa3b, v155
	v_exp_f32_e32 v0, v0
	s_nop 0
	v_add_f32_e32 v0, 1.0, v0
	v_rcp_f32_e32 v0, v0
	s_nop 0
	v_fmac_f32_e32 v159, v37, v0
	v_mul_f32_e32 v0, 0xbfb8aa3b, v157
	v_exp_f32_e32 v0, v0
	v_cvt_pk_bf16_f32 v155, v169, v159
	v_lshlrev_b64 v[158:159], 11, v[164:165]
	v_cvt_pk_bf16_f32 v156, v174, v160
	v_add_f32_e32 v0, 1.0, v0
	v_rcp_f32_e32 v0, v0
	v_lshl_add_u64 v[158:159], v[162:163], 0, v[158:159]
	v_lshlrev_b32_e32 v165, 16, v172
	v_and_b32_e32 v160, 0xffff0000, v170
	v_fmac_f32_e32 v161, v33, v0
	v_lshlrev_b32_e32 v0, 16, v150
	v_mul_f32_e32 v0, 0xbfb8aa3b, v0
	v_exp_f32_e32 v0, v0
	v_cvt_pk_bf16_f32 v157, v175, v161
	global_store_dwordx4 v[158:159], v[154:157], off nt
	v_and_b32_e32 v150, 0xffff0000, v150
	v_add_f32_e32 v0, 1.0, v0
	v_rcp_f32_e32 v0, v0
	v_lshlrev_b32_e32 v155, 16, v152
	v_lshlrev_b32_e32 v157, 16, v170
	v_and_b32_e32 v152, 0xffff0000, v152
	v_fmac_f32_e32 v157, v26, v0
	v_mul_f32_e32 v0, 0xbfb8aa3b, v155
	v_exp_f32_e32 v0, v0
	v_lshlrev_b32_e32 v154, 16, v151
	v_lshlrev_b32_e32 v156, 16, v153
	v_lshlrev_b32_e32 v161, 16, v171
	v_add_f32_e32 v0, 1.0, v0
	v_rcp_f32_e32 v0, v0
	v_and_b32_e32 v151, 0xffff0000, v151
	v_and_b32_e32 v153, 0xffff0000, v153
	v_and_b32_e32 v164, 0xffff0000, v171
	v_fmac_f32_e32 v165, v22, v0
	v_mul_f32_e32 v0, 0xbfb8aa3b, v150
	v_exp_f32_e32 v0, v0
	v_lshlrev_b32_e32 v155, 16, v143
	v_and_b32_e32 v143, 0xffff0000, v143
	v_add_f32_e32 v0, 1.0, v0
	v_rcp_f32_e32 v0, v0
	s_nop 0
	v_fmac_f32_e32 v160, v27, v0
	v_mul_f32_e32 v0, 0xbfb8aa3b, v152
	v_exp_f32_e32 v0, v0
	v_cvt_pk_bf16_f32 v150, v157, v160
	v_lshlrev_b32_e32 v157, 16, v145
; __device__ __forceinline__ float sigmoidf_(float g) { return __builtin_amdgcn_rcpf(1.f + __expf(-g)); }
; __device__ __forceinline__ u32x4 pack8(const f32x4& a, const f32x4& b) { u32x4 w; w.x = cvt_pk_bf16(a[0], a[1]); w.y = cvt_pk_bf16(a[2], a[3]); w.z = cvt_pk_bf16(b[0], b[1]); w.w = cvt_pk_bf16(b[2], b[3]); return w; }
; __device__ __forceinline__ void unpack8(const u32x4& w, float (&v)[8]) { v[0] = bf_lo(w.x); v[1] = bf_hi(w.x); v[2] = bf_lo(w.y); v[3] = bf_hi(w.y); v[4] = bf_lo(w.z); v[5] = bf_hi(w.z); v[6] = bf_lo(w.w); v[7] = bf_hi(w.w); }
;     __device__ __forceinline__ void apply(const Ld& d, int row, int c0, int, int, int, const f32x4& a0, const f32x4& b0, const f32x4& a1, const f32x4& b1) const { half(d.g0, row, c0, a0, b0); half(d.g1, row, c0 + 128, a1, b1); }
;     __device__ __forceinline__ void half(const u32x4& gw, const u32x4& pw, int row, int col, const f32x4& a, const f32x4& b) const {
;         float g[8]; unpack8(gw, g); float p[8]; unpack8(pw, p);
;         f32x4 r0, r1;
; #pragma unroll
;         for (int i = 0; i < 4; ++i) { r0[i] = a[i] * sigmoidf_(g[i]) + p[i]; r1[i] = b[i] * sigmoidf_(g[4 + i]) + p[4 + i]; }
;         *(u32x4*)(merged + (size_t)row * 1024 + col) = pack8(r0, r1);
;     }
;     __device__ __forceinline__ void apply(const Ld& d, int row, int c0, int, int, int, const f32x4& a0, const f32x4& b0, const f32x4& a1, const f32x4& b1) const { half(d.g0, d.p0, row, c0, a0, b0); half(d.g1, d.p1, row, c0 + 128, a1, b1); }
	v_and_b32_e32 v145, 0xffff0000, v145
	v_add_f32_e32 v0, 1.0, v0
	v_rcp_f32_e32 v0, v0
	s_nop 0
	v_fmac_f32_e32 v166, v23, v0
	v_mul_f32_e32 v0, 0xbfb8aa3b, v154
	v_exp_f32_e32 v0, v0
	v_lshlrev_b32_e32 v154, 16, v142
	v_and_b32_e32 v142, 0xffff0000, v142
	v_add_f32_e32 v0, 1.0, v0
	v_rcp_f32_e32 v0, v0
	s_nop 0
	v_fmac_f32_e32 v161, v28, v0
	v_mul_f32_e32 v0, 0xbfb8aa3b, v156
	v_exp_f32_e32 v0, v0
	v_lshlrev_b32_e32 v156, 16, v144
	v_and_b32_e32 v144, 0xffff0000, v144
	v_add_f32_e32 v0, 1.0, v0
	v_rcp_f32_e32 v0, v0
	s_nop 0
	v_fmac_f32_e32 v167, v24, v0
	v_mul_f32_e32 v0, 0xbfb8aa3b, v151
	v_exp_f32_e32 v0, v0
	s_nop 0
	v_add_f32_e32 v0, 1.0, v0
	v_rcp_f32_e32 v0, v0
	s_nop 0
	v_fmac_f32_e32 v164, v29, v0
	v_mul_f32_e32 v0, 0xbfb8aa3b, v153
	v_exp_f32_e32 v0, v0
	v_cvt_pk_bf16_f32 v151, v161, v164
	v_cvt_pk_bf16_f32 v152, v165, v166
	s_nop 0
	v_add_f32_e32 v0, 1.0, v0
	v_rcp_f32_e32 v0, v0
	s_nop 0
	v_fmac_f32_e32 v168, v25, v0
	v_lshlrev_b32_e32 v0, 16, v146
	v_mul_f32_e32 v0, 0xbfb8aa3b, v0
	v_exp_f32_e32 v0, v0
	v_cvt_pk_bf16_f32 v153, v167, v168
	global_store_dwordx4 v[158:159], v[150:153], off offset:256 nt
	v_and_b32_e32 v146, 0xffff0000, v146
	v_add_f32_e32 v0, 1.0, v0
	v_rcp_f32_e32 v0, v0
	v_lshlrev_b32_e32 v152, 16, v148
	v_and_b32_e32 v148, 0xffff0000, v148
	v_lshlrev_b32_e32 v151, 16, v147
	v_fmac_f32_e32 v154, v18, v0
	v_mul_f32_e32 v0, 0xbfb8aa3b, v152
	v_exp_f32_e32 v0, v0
	v_lshlrev_b32_e32 v153, 16, v149
	v_and_b32_e32 v147, 0xffff0000, v147
	v_and_b32_e32 v149, 0xffff0000, v149
	v_add_f32_e32 v0, 1.0, v0
	v_rcp_f32_e32 v0, v0
	v_add_u32_e32 v150, s0, v240
	v_fmac_f32_e32 v156, v10, v0
	v_mul_f32_e32 v0, 0xbfb8aa3b, v146
	v_exp_f32_e32 v0, v0
	s_nop 0
	v_add_f32_e32 v0, 1.0, v0
	v_rcp_f32_e32 v0, v0
	s_nop 0
	v_fmac_f32_e32 v142, v19, v0
	v_mul_f32_e32 v0, 0xbfb8aa3b, v148
	v_exp_f32_e32 v0, v0
	v_cvt_pk_bf16_f32 v142, v154, v142
	v_lshlrev_b32_e32 v148, 16, v135
	v_and_b32_e32 v135, 0xffff0000, v135
	v_add_f32_e32 v0, 1.0, v0
	v_rcp_f32_e32 v0, v0
	s_nop 0
	v_fmac_f32_e32 v144, v11, v0
	v_mul_f32_e32 v0, 0xbfb8aa3b, v151
	v_exp_f32_e32 v0, v0
	v_ashrrev_i32_e32 v151, 31, v150
	v_add_f32_e32 v0, 1.0, v0
	v_rcp_f32_e32 v0, v0
	s_nop 0
	v_fmac_f32_e32 v155, v20, v0
	v_mul_f32_e32 v0, 0xbfb8aa3b, v153
	v_exp_f32_e32 v0, v0
	s_nop 0
	v_add_f32_e32 v0, 1.0, v0
	v_rcp_f32_e32 v0, v0
	s_nop 0
	v_fmac_f32_e32 v157, v12, v0
	v_mul_f32_e32 v0, 0xbfb8aa3b, v147
	v_exp_f32_e32 v0, v0
	v_lshlrev_b64 v[146:147], 11, v[150:151]
	v_lshl_add_u64 v[146:147], v[162:163], 0, v[146:147]
	v_lshlrev_b32_e32 v150, 16, v137
	v_add_f32_e32 v0, 1.0, v0
	v_rcp_f32_e32 v0, v0
	v_and_b32_e32 v137, 0xffff0000, v137
	v_fmac_f32_e32 v143, v21, v0
	v_mul_f32_e32 v0, 0xbfb8aa3b, v149
	v_exp_f32_e32 v0, v0
	v_cvt_pk_bf16_f32 v143, v155, v143
	v_cvt_pk_bf16_f32 v144, v156, v144
	v_lshlrev_b32_e32 v149, 16, v136
	v_add_f32_e32 v0, 1.0, v0
	v_rcp_f32_e32 v0, v0
	v_and_b32_e32 v136, 0xffff0000, v136
	v_fmac_f32_e32 v145, v13, v0
	v_lshlrev_b32_e32 v0, 16, v138
	v_mul_f32_e32 v0, 0xbfb8aa3b, v0
	v_exp_f32_e32 v0, v0
	v_cvt_pk_bf16_f32 v145, v157, v145
	global_store_dwordx4 v[146:147], v[142:145], off nt
	v_and_b32_e32 v138, 0xffff0000, v138
	v_add_f32_e32 v0, 1.0, v0
	v_rcp_f32_e32 v0, v0
	v_lshlrev_b32_e32 v143, 16, v140
	v_lshlrev_b32_e32 v145, 16, v134
	v_and_b32_e32 v140, 0xffff0000, v140
	v_fmac_f32_e32 v145, v6, v0
	v_mul_f32_e32 v0, 0xbfb8aa3b, v143
	v_exp_f32_e32 v0, v0
	v_and_b32_e32 v134, 0xffff0000, v134
	v_lshlrev_b32_e32 v142, 16, v139
	v_lshlrev_b32_e32 v144, 16, v141
	v_add_f32_e32 v0, 1.0, v0
	v_rcp_f32_e32 v0, v0
	v_and_b32_e32 v139, 0xffff0000, v139
	v_and_b32_e32 v141, 0xffff0000, v141
	v_fmac_f32_e32 v149, v2, v0
	v_mul_f32_e32 v0, 0xbfb8aa3b, v138
	v_exp_f32_e32 v0, v0
	s_nop 0
	v_add_f32_e32 v0, 1.0, v0
	v_rcp_f32_e32 v0, v0
	s_nop 0
	v_fmac_f32_e32 v134, v7, v0
	v_mul_f32_e32 v0, 0xbfb8aa3b, v140
	v_exp_f32_e32 v0, v0
	v_cvt_pk_bf16_f32 v134, v145, v134
	s_nop 0
	v_add_f32_e32 v0, 1.0, v0
	v_rcp_f32_e32 v0, v0
	s_nop 0
	v_fmac_f32_e32 v136, v3, v0
	v_mul_f32_e32 v0, 0xbfb8aa3b, v142
	v_exp_f32_e32 v0, v0
	s_nop 0
	v_add_f32_e32 v0, 1.0, v0
	v_rcp_f32_e32 v0, v0
	s_nop 0
	v_fmac_f32_e32 v148, v8, v0
	v_mul_f32_e32 v0, 0xbfb8aa3b, v144
	v_exp_f32_e32 v0, v0
	s_nop 0
	v_add_f32_e32 v0, 1.0, v0
	v_rcp_f32_e32 v0, v0
	s_nop 0
	v_fmac_f32_e32 v150, v4, v0
	v_mul_f32_e32 v0, 0xbfb8aa3b, v139
	v_exp_f32_e32 v0, v0
	s_nop 0
	v_add_f32_e32 v0, 1.0, v0
	v_rcp_f32_e32 v0, v0
	s_nop 0
	v_fmac_f32_e32 v135, v9, v0
	v_mul_f32_e32 v0, 0xbfb8aa3b, v141
	v_exp_f32_e32 v0, v0
	v_cvt_pk_bf16_f32 v135, v148, v135
	v_cvt_pk_bf16_f32 v136, v149, v136
	s_nop 0
	v_add_f32_e32 v0, 1.0, v0
	v_rcp_f32_e32 v0, v0
	s_nop 0
	v_fmac_f32_e32 v137, v5, v0
	v_cvt_pk_bf16_f32 v137, v150, v137
	global_store_dwordx4 v[146:147], v[134:137], off offset:256 nt
